# MLP-up tile schedule: the 32 padded-row tiles (slow statistics epilogue) run in round 1 on workgroups 224-255 (which have slack) instead of 4 of them closing the critical last round; plus previous sta
# speedup vs baseline: 1.0151x; 1.0017x over previous
.LBB0_59:
	s_or_b64 exec, exec, s[4:5]
	s_add_u32 s4, s76, 0x800
	s_addc_u32 s5, s77, 0
	v_writelane_b32 v252, s4, 39
	s_add_u32 s3, s76, 0x10120000
	v_lshrrev_b32_e32 v165, 4, v164
	v_writelane_b32 v252, s5, 40
	v_writelane_b32 v252, s3, 41
	s_addc_u32 s3, s77, 0
	v_writelane_b32 v252, s3, 42
	s_add_u32 s3, s76, 0x10340000
	v_writelane_b32 v252, s3, 43
	s_addc_u32 s3, s77, 0
	s_add_u32 s4, s76, 0x1300000
	v_writelane_b32 v252, s3, 44
	s_addc_u32 s5, s77, 0
	v_writelane_b32 v252, s4, 45
	v_mbcnt_lo_u32_b32 v209, -1, 0
	v_lshl_add_u32 v204, v164, 4, 0
	v_writelane_b32 v252, s5, 46
	s_add_u32 s4, s76, 0x1b00000
	s_addc_u32 s5, s77, 0
	v_writelane_b32 v252, s4, 47
	v_mov_b32_e32 v205, 0x358637bd
	v_mov_b32_e32 v211, 1
	v_writelane_b32 v252, s5, 48
	s_add_u32 s4, s76, 0x3b00000
	s_addc_u32 s5, s77, 0
	v_writelane_b32 v252, s4, 49
	v_mov_b32_e32 v208, 0x3c23d70a
	v_mbcnt_hi_u32_b32 v210, -1, v209
	v_writelane_b32 v252, s5, 50
	s_add_u32 s4, s76, 0x5b00000
	s_addc_u32 s5, s77, 0
	v_writelane_b32 v252, s4, 51
	v_mov_b32_e32 v112, 0
	v_mov_b32_e32 v212, 0xf149f2ca
	v_writelane_b32 v252, s5, 52
	s_add_u32 s4, s76, 0x7300000
	s_addc_u32 s5, s77, 0
	v_writelane_b32 v252, s4, 53
	v_mov_b64_e32 v[174:175], 0xff
	v_mov_b64_e32 v[176:177], 0x420
	v_writelane_b32 v252, s5, 54
	s_add_u32 s4, s76, 0x7b00000
	s_addc_u32 s5, s77, 0
	v_writelane_b32 v252, s4, 55
	v_mov_b64_e32 v[178:179], 0x41f
	v_mov_b64_e32 v[180:181], 0x140
	v_writelane_b32 v252, s5, 56
	s_add_u32 s4, s76, 0x9b00000
	s_addc_u32 s5, s77, 0
	s_add_u32 s10, s76, 0x12100000
	s_addc_u32 s11, s77, 0
	s_add_u32 s86, s76, 0x16500000
	v_writelane_b32 v252, s4, 57
	s_addc_u32 s87, s77, 0
	v_mov_b64_e32 v[182:183], 0x13f
	v_writelane_b32 v252, s5, 58
	s_add_u32 s4, s76, 0x18700000
	s_addc_u32 s5, s77, 0
	v_writelane_b32 v252, s4, 59
	s_add_u32 s26, s76, 0x1a900000
	s_addc_u32 s27, s77, 0
	v_writelane_b32 v252, s5, 60
	s_ashr_i32 s31, s82, 31
	v_readlane_b32 s36, v252, 23
	s_ashr_i32 s3, s2, 31
	v_readlane_b32 s44, v252, 31
	v_readlane_b32 s45, v252, 32
	s_add_u32 s4, s44, 0x4000000
	s_addc_u32 s5, s45, 0
	v_readlane_b32 s37, v252, 24
	v_readlane_b32 s38, v252, 25
	v_readlane_b32 s39, v252, 26
	v_readlane_b32 s40, v252, 27
	v_readlane_b32 s41, v252, 28
	v_readlane_b32 s42, v252, 29
	v_readlane_b32 s43, v252, 30
	v_readlane_b32 s46, v252, 33
	v_readlane_b32 s47, v252, 34
	v_readlane_b32 s48, v252, 35
	v_readlane_b32 s49, v252, 36
	v_readlane_b32 s50, v252, 37
	v_readlane_b32 s51, v252, 38
	v_writelane_b32 v252, s4, 61
	s_add_u32 s18, s42, 0x2000
	s_addc_u32 s19, s43, 0
	v_writelane_b32 v252, s5, 62
	s_movk_i32 s91, 0x6000
	v_readlane_b32 s34, v252, 22
	s_lshl_b32 s74, s34, 2
	s_cmp_lg_u64 s[42:43], 0
	s_cselect_b64 s[20:21], -1, 0
	s_add_u32 s84, s76, 0x40200
	s_addc_u32 s85, s77, 0
	s_add_u32 s58, s76, 0x40400
	s_addc_u32 s59, s77, 0
	s_add_u32 s60, s76, 0x40500
	s_addc_u32 s61, s77, 0
	s_add_u32 s62, s76, 0x40600
	s_addc_u32 s63, s77, 0
	s_add_u32 s56, s76, 0x40700
	s_addc_u32 s57, s77, 0
	s_add_u32 s22, s76, 0x40800
	s_addc_u32 s23, s77, 0
	s_add_u32 s4, s76, 0x40900
	s_addc_u32 s5, s77, 0
	v_writelane_b32 v252, s4, 63
	v_writelane_b32 v255, s84, 0
	s_movk_i32 s94, 0x1fff
	v_writelane_b32 v253, s5, 0
	s_add_u32 s4, s76, 0x40a00
	s_addc_u32 s5, s77, 0
	v_writelane_b32 v253, s4, 1
	v_writelane_b32 v255, s85, 1
	v_writelane_b32 v255, s58, 2
	v_writelane_b32 v253, s5, 2
	s_add_u32 s4, s76, 0x40b00
	s_addc_u32 s5, s77, 0
	v_writelane_b32 v253, s4, 3
	v_writelane_b32 v255, s59, 3
	v_writelane_b32 v255, s60, 4
	v_writelane_b32 v253, s5, 4
	s_add_u32 s4, s76, 0x40c00
	s_addc_u32 s5, s77, 0
	v_writelane_b32 v253, s4, 5
	v_writelane_b32 v255, s61, 5
	v_writelane_b32 v255, s62, 6
	v_writelane_b32 v253, s5, 6
	s_add_u32 s4, s76, 0x40d00
	s_addc_u32 s5, s77, 0
	v_writelane_b32 v253, s4, 7
	v_writelane_b32 v255, s63, 7
	v_writelane_b32 v255, s56, 8
	v_writelane_b32 v253, s5, 8
	s_add_u32 s4, s76, 0x40e00
	s_addc_u32 s5, s77, 0
	v_writelane_b32 v253, s4, 9
	v_writelane_b32 v255, s57, 9
	s_nop 0
	v_writelane_b32 v253, s5, 10
	s_add_u32 s4, s76, 0x40f00
	s_addc_u32 s5, s77, 0
	v_writelane_b32 v253, s4, 11
	s_nop 1
	v_writelane_b32 v253, s5, 12
	s_add_u32 s4, s76, 0x41000
	s_addc_u32 s5, s77, 0
	v_writelane_b32 v253, s4, 13
	s_nop 1
	v_writelane_b32 v253, s5, 14
	s_add_u32 s4, s76, 0x41100
	s_addc_u32 s5, s77, 0
	v_writelane_b32 v253, s4, 15
	s_nop 1
	v_writelane_b32 v253, s5, 16
	s_add_u32 s4, s76, 0x41200
	s_addc_u32 s5, s77, 0
	v_writelane_b32 v253, s4, 17
	s_nop 1
	v_writelane_b32 v253, s5, 18
	s_add_u32 s4, s76, 0x41300
	s_addc_u32 s5, s77, 0
	v_writelane_b32 v253, s4, 19
	s_cmp_eq_u32 s8, 15
	s_nop 0
	v_writelane_b32 v253, s5, 20
	s_cselect_b64 s[4:5], -1, 0
	v_writelane_b32 v253, s4, 21
	s_cmp_eq_u32 s8, 14
	s_nop 0
	v_writelane_b32 v253, s5, 22
	s_cselect_b64 s[4:5], -1, 0
	v_writelane_b32 v253, s4, 23
	s_cmp_eq_u32 s8, 13
	s_nop 0
	v_writelane_b32 v253, s5, 24
	s_cselect_b64 s[4:5], -1, 0
	v_writelane_b32 v253, s4, 25
	s_cmp_eq_u32 s8, 12
	s_nop 0
	v_writelane_b32 v253, s5, 26
	s_cselect_b64 s[4:5], -1, 0
	v_writelane_b32 v253, s4, 27
	s_cmp_eq_u32 s8, 11
	s_nop 0
	v_writelane_b32 v253, s5, 28
	s_cselect_b64 s[4:5], -1, 0
	v_writelane_b32 v253, s4, 29
	s_cmp_eq_u32 s8, 10
	s_nop 0
	v_writelane_b32 v253, s5, 30
	s_cselect_b64 s[4:5], -1, 0
	v_writelane_b32 v253, s4, 31
	s_cmp_eq_u32 s8, 9
	s_nop 0
	v_writelane_b32 v253, s5, 32
	s_cselect_b64 s[4:5], -1, 0
	v_writelane_b32 v253, s4, 33
	s_cmp_eq_u32 s8, 8
	s_nop 0
	v_writelane_b32 v253, s5, 34
	s_cselect_b64 s[4:5], -1, 0
	v_writelane_b32 v253, s4, 35
	s_cmp_eq_u32 s8, 7
	s_nop 0
	v_writelane_b32 v253, s5, 36
	s_cselect_b64 s[4:5], -1, 0
	v_writelane_b32 v253, s4, 37
	s_cmp_eq_u32 s8, 6
	s_nop 0
	v_writelane_b32 v253, s5, 38
	s_cselect_b64 s[4:5], -1, 0
	v_writelane_b32 v253, s4, 39
	s_cmp_eq_u32 s8, 5
	s_nop 0
	v_writelane_b32 v253, s5, 40
	s_cselect_b64 s[4:5], -1, 0
	v_writelane_b32 v253, s4, 41
	s_cmp_eq_u32 s8, 4
	s_nop 0
	v_writelane_b32 v253, s5, 42
	s_cselect_b64 s[4:5], -1, 0
	v_writelane_b32 v253, s4, 43
	s_cmp_eq_u32 s8, 3
	s_nop 0
	v_writelane_b32 v253, s5, 44
	s_cselect_b64 s[4:5], -1, 0
	v_writelane_b32 v253, s4, 45
	s_cmp_eq_u32 s8, 2
	s_nop 0
	v_writelane_b32 v253, s5, 46
	s_cselect_b64 s[4:5], -1, 0
	v_writelane_b32 v253, s4, 47
	s_cmp_eq_u32 s8, 1
	s_nop 0
	v_writelane_b32 v253, s5, 48
	s_cselect_b64 s[4:5], -1, 0
	v_writelane_b32 v253, s4, 49
	s_cmp_eq_u32 s8, 0
	s_nop 0
	v_writelane_b32 v253, s5, 50
	s_cselect_b64 s[4:5], -1, 0
	v_writelane_b32 v253, s4, 51
	s_nop 1
	v_writelane_b32 v253, s5, 52
	s_lshl_b32 s4, s9, 2
	s_add_u32 s4, s16, s4
	s_addc_u32 s5, s17, 0
	s_add_u32 s6, s4, 0x1400
	s_addc_u32 s7, s5, 0
	v_writelane_b32 v253, s6, 53
	s_add_u32 s4, s4, 0x2400
	s_addc_u32 s5, s5, 0
	v_writelane_b32 v253, s7, 54
	v_writelane_b32 v253, s4, 55
	s_nop 1
	v_writelane_b32 v253, s5, 56
	s_add_u32 s4, s76, 0x43400
	s_addc_u32 s5, s77, 0
	v_writelane_b32 v253, s4, 57
	s_nop 1
	v_writelane_b32 v253, s5, 58
	s_add_u32 s4, s76, 0x43500
	s_addc_u32 s5, s77, 0
	v_writelane_b32 v253, s4, 59
	s_lshr_b32 s6, s25, 7
	s_bfe_u32 s7, s25, 0x10006
	v_writelane_b32 v253, s5, 60
	s_lshl_b32 s4, s34, 4
	s_and_b32 s28, s4, 0x3fffffe0
	s_lshl_b32 s4, s6, 14
	s_add_i32 s4, s4, 0
	v_writelane_b32 v253, s4, 61
	s_lshl_b32 s4, s2, 9
	v_writelane_b32 v253, s4, 62
	s_lshl_b32 s5, s7, 1
	s_lshl_b32 s4, s7, 6
	s_lshl_b32 s90, s7, 14
	s_add_i32 s29, 0, 0x20080
	s_and_b32 s8, 64, s25
	s_lshl_b32 s36, s82, 9
	s_cmp_eq_u32 s7, 0
	s_cselect_b64 s[12:13], -1, 0
	s_cmp_lg_u32 s8, 0
	v_writelane_b32 v253, s12, 63
	s_cselect_b64 s[8:9], -1, 0
	s_lshl_b32 s6, s6, 5
	v_writelane_b32 v254, s13, 0
	v_writelane_b32 v254, s8, 1
	s_cmpk_lt_i32 s2, 0x120
	v_lshl_add_u32 v203, v164, 2, s29
	v_writelane_b32 v254, s9, 2
	v_writelane_b32 v254, s6, 3
	s_cselect_b64 s[6:7], -1, 0
	v_writelane_b32 v254, s6, 4
	s_lshl_b32 s14, s2, 3
	s_add_i32 s16, s34, s14
	v_writelane_b32 v254, s7, 5
	s_lshr_b32 s6, s3, 29
	s_add_i32 s6, s2, s6
	s_ashr_i32 s30, s6, 3
	s_lshl_b32 s7, s2, 5
	s_mul_i32 s8, s30, 0xffffff01
	s_add_i32 s7, s8, s7
	s_ashr_i32 s8, s7, 31
	s_lshr_b32 s8, s8, 26
	s_add_i32 s8, s7, s8
	s_and_b32 s9, s8, 0xffffffc0
	s_sub_i32 s7, s7, s9
	s_bfe_i32 s9, s7, 0x80000
	s_bfe_u32 s9, s9, 0x3000c
	s_add_i32 s9, s7, s9
	s_and_b32 s12, s9, 0xf8
	s_sub_i32 s7, s7, s12
	s_ashr_i32 s8, s8, 6
	s_lshl_b32 s8, s8, 3
	s_sext_i32_i8 s7, s7
	s_add_i32 s8, s8, s7
	s_bfe_i32 s7, s9, 0x80000
	s_sext_i32_i16 s7, s7
	s_and_b32 s9, s2, 3
	s_lshl_b32 s14, s16, 6
	s_ashr_i32 s7, s7, 3
	s_bfe_u32 s12, s2, 0x30002
	s_lshl_b32 s13, s9, 10
	s_lshl_b32 s73, s82, 3
	v_writelane_b32 v254, s14, 6
	s_mov_b32 s14, s16
	v_writelane_b32 v254, s14, 7
	s_cmpk_lt_i32 s16, 0x800
	s_nop 0
	v_writelane_b32 v254, s15, 8
	s_cselect_b64 s[14:15], -1, 0
	v_writelane_b32 v254, s14, 9
	s_cmpk_lt_i32 s2, 0x420
	s_nop 0
	v_writelane_b32 v254, s15, 10
	s_cselect_b64 s[14:15], -1, 0
	s_and_b32 s6, s6, -8
	v_writelane_b32 v254, s14, 11
	s_sub_i32 s33, s2, s6
	s_nop 0
	v_writelane_b32 v254, s15, 12
	s_add_u32 s14, s46, 0x4000000
	s_addc_u32 s15, s47, 0
	v_readlane_b32 s40, v252, 0
	v_readlane_b32 s52, v252, 12
	v_readlane_b32 s53, v252, 13
	v_readlane_b32 s50, v252, 10
	v_readlane_b32 s51, v252, 11
	s_cmp_lg_u64 s[52:53], 0
	v_writelane_b32 v254, s14, 13
	s_cselect_b64 s[50:51], -1, 0
	s_cmpk_lt_i32 s2, 0x140
	v_writelane_b32 v254, s15, 14
	s_cselect_b64 s[14:15], -1, 0
	v_writelane_b32 v254, s14, 15
	s_bfe_u32 s6, s25, 0x30006
	s_lshl_b32 s17, s6, 8
	v_writelane_b32 v254, s15, 16
	s_and_b32 s14, s2, 7
	v_writelane_b32 v254, s17, 17
	s_lshl_b32 s17, s6, 2
	v_readlane_b32 s54, v252, 14
	v_readlane_b32 s55, v252, 15
	s_bfe_u32 s15, s2, 0x30003
	s_lshl_b32 s16, s14, 11
	v_writelane_b32 v254, s17, 18
	s_lshl_b32 s17, s6, 20
	s_mov_b64 s[54:55], s[22:23]
	s_add_u32 s22, s26, s17
	s_addc_u32 s23, s27, 0
	s_cmp_lt_i32 s33, 0
	s_movk_i32 s17, 0x85
	s_movk_i32 s17, 0x80
	s_mul_i32 s17, s33, s17
	v_writelane_b32 v254, s22, 19
	s_add_i32 s17, s17, s30
	s_add_i32 s22, s2, 0x320
	s_cmpk_ge_u32 s2, 0xe0
	s_cselect_b32 s17, s22, s17
	v_writelane_b32 v255, s54, 10
	v_writelane_b32 v254, s23, 20
	s_ashr_i32 s22, s17, 31
	s_lshr_b32 s22, s22, 24
	s_add_i32 s22, s17, s22
	s_and_b32 s23, s22, 0xffffff00
	s_ashr_i32 s22, s22, 8
	s_lshl_b32 s22, s22, 3
	s_sub_i32 s17, s17, s23
	s_sub_i32 s23, 33, s22
	s_min_i32 s23, s23, 8
	v_writelane_b32 v254, s33, 21
	s_cmpk_lt_i32 s2, 0x100
	v_writelane_b32 v254, s30, 22
	s_cselect_b32 s88, 0, s13
	v_writelane_b32 v254, s88, 23
	s_cselect_b32 s12, s7, s12
	s_cselect_b32 s7, s7, s15
	v_writelane_b32 v254, s89, 24
	v_writelane_b32 v254, s12, 25
	v_writelane_b32 v254, s7, 26
	s_cselect_b32 s7, s8, 32
	v_writelane_b32 v254, s7, 27
	s_cselect_b32 s7, -1, s9
	v_writelane_b32 v254, s7, 28
	s_cselect_b32 s7, -1, s14
	v_writelane_b32 v254, s7, 29
	s_cselect_b32 s7, 32, 8
	v_writelane_b32 v254, s7, 30
	s_cselect_b32 s7, 0x80, 16
	v_writelane_b32 v254, s7, 31
	s_sext_i32_i16 s7, s23
	v_cvt_f32_i32_e32 v0, s7
	v_cvt_f32_i32_e32 v1, s17
	s_cselect_b32 s88, 0, s16
	s_lshl_b32 s6, s6, 21
	v_rcp_iflag_f32_e32 v2, v0
	s_add_u32 s8, s26, s6
	v_writelane_b32 v254, s26, 32
	s_addc_u32 s9, s27, 0
	v_mul_f32_e32 v2, v1, v2
	v_writelane_b32 v254, s27, 33
	s_xor_b32 s6, s17, s7
	v_trunc_f32_e32 v2, v2
	v_writelane_b32 v254, s8, 34
	s_ashr_i32 s6, s6, 30
	v_fma_f32 v1, -v2, v0, v1
	v_writelane_b32 v254, s9, 35
	s_or_b32 s8, s6, 1
	v_cmp_ge_f32_e64 s[6:7], |v1|, |v0|
	v_cvt_i32_f32_e32 v0, v2
	s_and_b64 s[6:7], s[6:7], exec
	s_mul_i32 s6, s83, s82
	s_mul_i32 s6, s6, s24
	v_writelane_b32 v254, s6, 36
	s_cselect_b32 s6, s8, 0
	v_readfirstlane_b32 s7, v0
	s_add_i32 s6, s7, s6
	s_mul_i32 s7, s6, s23
	s_sub_i32 s7, s17, s7
	s_sext_i32_i16 s7, s7
	s_add_i32 s7, s22, s7
	v_writelane_b32 v254, s7, 37
	v_writelane_b32 v254, s29, 38
	s_sext_i32_i16 s6, s6
	v_writelane_b32 v254, s6, 39
	s_lshl_b32 s6, s34, 7
	v_writelane_b32 v254, s6, 40
	s_add_u32 s6, s76, 0x1a740000
	s_addc_u32 s7, s77, 0
	v_writelane_b32 v254, s6, 41
	s_lshl_b32 s5, s5, 2
	s_lshl_b32 s4, s4, 1
	v_writelane_b32 v254, s7, 42
	v_writelane_b32 v254, s5, 43
	v_writelane_b32 v254, s28, 44
	s_add_i32 s5, s28, 0x800
	v_writelane_b32 v254, s5, 45
	s_add_i32 s5, 0, 0x20040
	v_writelane_b32 v254, s5, 46
	s_add_i32 s5, 0, 0x20044
	v_writelane_b32 v254, s5, 47
	v_writelane_b32 v254, s4, 48
	v_cmp_gt_u32_e64 s[6:7], 3, v164
	s_ashr_i32 s37, s36, 31
	v_writelane_b32 v254, s5, 49
	s_add_i32 s4, 0, 0x20084
	v_writelane_b32 v254, s4, 50
	v_writelane_b32 v254, s6, 51
	s_lshl_b64 s[64:65], s[36:37], 4
	v_writelane_b32 v255, s55, 11
	v_writelane_b32 v254, s7, 52
	v_writelane_b32 v254, s88, 53
	s_lshl_b64 s[6:7], s[36:37], 7
	v_xor_b32_e32 v0, v165, v164
	v_writelane_b32 v254, s89, 54
	v_writelane_b32 v254, s6, 55
	v_writelane_b32 v255, s64, 12
	v_lshlrev_b32_e32 v1, 3, v0
	v_writelane_b32 v254, s7, 56
	s_mov_b64 s[6:7], -1
	v_writelane_b32 v254, s6, 57
	s_lshl_b64 s[92:93], s[36:37], 2
	v_writelane_b32 v255, s65, 13
	v_writelane_b32 v254, s7, 58
	v_writelane_b32 v254, s72, 59
	v_writelane_b32 v254, s73, 60
	v_writelane_b32 v254, s86, 61
	v_and_b32_e32 v2, 56, v1
	v_mov_b32_e32 v0, 0
	v_and_b32_e32 v4, 0x78, v1
	v_writelane_b32 v254, s87, 62
	v_writelane_b32 v255, s92, 14
	v_mov_b32_e32 v113, v0
	v_mov_b32_e32 v114, v0
	v_mov_b32_e32 v115, v0
	v_lshlrev_b32_e32 v166, 1, v4
	v_lshlrev_b32_e32 v168, 1, v2
	s_mov_b32 s83, 0xffff0000
	s_mov_b32 s12, 0x800000
	s_movk_i32 s13, 0x4400
	s_add_i32 s33, 0, 0x20000
	s_mov_b32 s22, 0x40000
	s_movk_i32 s23, 0x7fff
	s_mov_b32 s24, 0x80000
	s_mov_b32 s25, 0xc0000
	s_mov_b32 s29, 0x100000
	s_mov_b32 s14, 0x140000
	s_mov_b32 s15, 0x180000
	s_mov_b32 s28, 0x1c0000
	s_mov_b32 s30, 0x3e38aa3b
	s_mov_b32 s52, 0xf149f2ca
	s_mov_b32 s53, 0xc2800000
	s_mov_b64 s[4:5], 0
	s_mov_b64 s[26:27], 0x80
	s_mov_b32 s66, s89
	v_writelane_b32 v254, s74, 63
	v_writelane_b32 v255, s93, 15
	v_readlane_b32 s41, v252, 1
	v_readlane_b32 s42, v252, 2
	v_readlane_b32 s43, v252, 3
	v_readlane_b32 s44, v252, 4
	v_readlane_b32 s45, v252, 5
	v_readlane_b32 s46, v252, 6
	v_readlane_b32 s47, v252, 7
	v_readlane_b32 s48, v252, 8
	v_readlane_b32 s49, v252, 9
	s_branch .LBB0_63

.LBB0_705:
	s_add_i32 s62, s62, 1
	s_mul_i32 s38, s62, s31
	s_mul_hi_u32 s39, s62, s82
	s_add_i32 s39, s39, s38
	s_mul_i32 s38, s62, s82
	s_add_u32 s46, s38, s2
	s_addc_u32 s47, s39, s3
	v_cmp_gt_i64_e32 vcc, s[46:47], v[178:179]
	v_cmp_lt_i64_e64 s[38:39], s[46:47], v[176:177]
	s_cbranch_vccnz .LBB0_707
	s_sub_i32 s46, s46, 32
	s_ashr_i32 s41, s46, 31
	s_lshr_b32 s41, s41, 29
	s_add_i32 s41, s46, s41
	s_ashr_i32 s42, s41, 3
	s_and_b32 s41, s41, -8
	s_sub_i32 s41, s46, s41
	s_cmp_lt_i32 s41, 0
	s_movk_i32 s43, 0x80
	s_mul_i32 s41, s41, s43
	s_add_i32 s41, s41, s42
	s_ashr_i32 s42, s41, 31
	s_lshr_b32 s42, s42, 24
	s_add_i32 s42, s41, s42
	s_ashr_i32 s43, s42, 8
	s_lshl_b32 s43, s43, 3
	s_sub_i32 s44, 33, s43
	s_min_i32 s44, s44, 8
	s_abs_i32 s45, s44
	v_cvt_f32_u32_e32 v2, s45
	s_sub_i32 s47, 0, s45
	s_and_b32 s42, s42, 0xffffff00
	s_sub_i32 s41, s41, s42
	v_rcp_iflag_f32_e32 v2, v2
	s_abs_i32 s42, s41
	s_xor_b32 s46, s41, s44
	s_ashr_i32 s46, s46, 31
	v_mul_f32_e32 v2, 0x4f7ffffe, v2
	v_cvt_u32_f32_e32 v2, v2
	s_nop 0
	v_readfirstlane_b32 s48, v2
	s_mul_i32 s47, s47, s48
	s_mul_hi_u32 s47, s48, s47
	s_add_i32 s48, s48, s47
	s_mul_hi_u32 s47, s42, s48
	s_mul_i32 s48, s47, s45
	s_sub_i32 s42, s42, s48
	s_add_i32 s49, s47, 1
	s_sub_i32 s48, s42, s45
	s_cmp_ge_u32 s42, s45
	s_cselect_b32 s47, s49, s47
	s_cselect_b32 s42, s48, s42
	s_add_i32 s48, s47, 1
	s_cmp_ge_u32 s42, s45
	s_cselect_b32 s42, s48, s47
	s_xor_b32 s42, s42, s46
	s_sub_i32 s42, s42, s46
	s_mul_i32 s44, s42, s44
	s_sub_i32 s41, s41, s44
	s_add_i32 s44, s41, s43
